# single-pass attention epilogue combined with early stores in the bf16 residual fast paths
# speedup vs baseline: 1.0135x; 1.0015x over previous
; __device__ __forceinline__ int crow(int r, int hi) { return (r & 3) + 8 * (r >> 2) + 4 * hi; }
; #define AT_LOAD(K0, K1, V0, V1, T) do { const size_t e_ = (size_t)(128 * (T) + sr) * 64 + sc; \
;         K0 = *(const bf16x8*)(kcp + e_); V0 = *(const bf16x8*)(vcp + e_); K1 = *(const bf16x8*)(kcp + e_ + 64 * 64); V1 = *(const bf16x8*)(vcp + e_ + 64 * 64); } while (0)
; #define AT_STORE(K0, K1, V0, V1, BUF) do { *(LAS bf16x8*)(lds + AT_K + (BUF) * AT_KB + kst0) = K0; *(LAS bf16x8*)(lds + AT_K + (BUF) * AT_KB + kst1) = K1; \
;         *(LAS bf16x8*)(lds + AT_V + (BUF) * AT_VB + vst0) = V0; *(LAS bf16x8*)(lds + AT_V + (BUF) * AT_VB + vst1) = V1; } while (0)
; template <int VAR>
; __device__ __forceinline__ void attn_unit(const Args& a, int l, int b, int h, int qrow0  , bool ctxu, const bf16* Z, bf16* Y, LAS unsigned char* lds) {
;     ...
;     for (int t = 0; t < NT; t += 2) {
;         __syncthreads();
;         if (t + 2 < NT) AT_LOAD(ka0, ka1, va0, va1, t + 2);
;         attn_tile(Kb0, vb0, q0, q1, negm, m, o0, o1, lacc, t == 0, wsf, r32, hi);
;         AT_STORE(kb0, kb1, vb0_, vb1_, 1);
;         __syncthreads();
;         if (t + 3 < NT) AT_LOAD(kb0, kb1, vb0_, vb1_, t + 3);
;         attn_tile(Kb0 + AT_KB, vb0 + AT_VB, q0, q1, negm, m, o0, o1, lacc, false, wsf, r32, hi);
;         if (t + 2 < NT) AT_STORE(ka0, ka1, va0, va1, 0);
;     }
;     ...
;     if (comp == 0) {
; #pragma unroll
;         for (int r = 0; r < 16; ++r) { const int qr = crow(r, hi); const float il = __builtin_amdgcn_rcpf(lacc[r]); o0[r] = o0[r] * il - stg[qr * 64 + r32]; o1[r] = o1[r] * il - stg[qr * 64 + 32 + r32]; }
;         asm volatile("s_waitcnt lgkmcnt(0)" ::: "memory");
; #pragma unroll
;         for (int r = 0; r < 16; ++r) { const int qr = crow(r, hi); stg[qr * 64 + r32] = o0[r]; stg[qr * 64 + 32 + r32] = o1[r]; }
;         asm volatile("s_waitcnt lgkmcnt(0)" ::: "memory");
;         const int ch = lane & 7;
;         float gsub[8];
; #pragma unroll
;         for (int i = 0; i < 8; ++i) gsub[i] = a.subln_g[l * 64 + ch * 8 + i] * omli;
.Lat_ndg5:
	ds_read_b128 v[48:51], v144 offset:0
	ds_read_b128 v[52:55], v145 offset:0
	ds_read_b128 v[56:59], v144 offset:4096
	ds_read_b128 v[60:63], v145 offset:4096
	v_mfma_f32_32x32x16_bf16 v[80:95], v[162:165], v[192:195], v[80:95]
	v_mfma_f32_32x32x16_bf16 v[200:215], v[162:165], v[196:199], v[200:215]
	s_add_u32 s33, s33, 1
	s_cmp_lt_u32 s33, 22
	s_cbranch_scc1 .Lat_loop
	v_add_f32_e32 v132, v128, v129
	v_mov_b32_e32 v133, v132
	s_nop 1
	v_permlane32_swap_b32_e32 v132, v133
	v_add_f32_e32 v135, v132, v133
	v_add_f32_e32 v132, v130, v131
	v_mov_b32_e32 v133, v132
	s_nop 1
	v_permlane32_swap_b32_e32 v132, v133
	v_add_f32_e32 v130, v132, v133
	s_nop 7
	s_waitcnt lgkmcnt(0)
	ds_write_b32 v148, v135
	s_waitcnt lgkmcnt(0)
	ds_read_b128 v[32:35], v147 offset:0
	ds_read_b128 v[36:39], v147 offset:32
	ds_read_b128 v[40:43], v147 offset:64
	ds_read_b128 v[44:47], v147 offset:96
	s_waitcnt lgkmcnt(0)
	s_bfe_u32 s9, s29, 0x20006
	s_ashr_i32 s8, s29, 8
	s_mov_b32 s93, 0
	s_waitcnt vmcnt(0)
	v_or_b32_e32 v132, s58, v228
	v_mov_b32_e32 v133, 0
	v_lshl_add_u64 v[132:133], v[132:133], 2, s[78:79]
	global_load_dwordx4 v[100:103], v[132:133], off offset:16
	global_load_dwordx4 v[96:99], v[132:133], off
	s_setprio 0
	s_branch .LBB0_459
